# P8 and P4 sample-panel residual epilogues batched/pipelined too (on top of P11 epilogues)
# speedup vs baseline: 1.0116x; 1.0052x over previous
;     static __device__ __forceinline__ const void* rowptr(const void* b, size_t r, int ldc) { if constexpr (BASE_BF16) return (const bf16_t*)b + r * ldc; else return (const float*)b + r * ldc; }
;     static __device__ __forceinline__ void stq(bf16_t* p, f32x4 v) { u32x2 w; w.x = cvt_pk_bf16(v[0], v[1]); w.y = cvt_pk_bf16(v[2], v[3]); *(u32x2*)p = w; }
;     __device__ __forceinline__ void operator()(const f32x4 (&acc)[2][2][4][2], const Unit& u, int wr, int wc, int fr, int fq) const {
;     ...
;             for (int ai = 0; ai < 2; ++ai)
; #pragma unroll
;                 for (int m = 0; m < 4; ++m) { const int r = u.pm * BM + ai * HALF + wr * 64 + m * 16 + fr;
;                     const void* brow = (r < split_rows) ? rowptr(base_p, (size_t)r, ldc) : rowptr(base_s, (size_t)(r - split_rows), ldc);
;                     const float* grow = mod + (size_t)((r < split_rows) ? 0 : 1 + ((r - split_rows) >> 3)) * modld + goff;
;                     bf16_t* orow = out + (size_t)r * ldc;
; #pragma unroll
;                     for (int bj = 0; bj < 2; ++bj)
; #pragma unroll
;                         for (int n = 0; n < 2; ++n) { const int c = col0 + bj * HALF + n * 16;
;                             const f32x4 b = ldb(brow, c), g = *(const f32x4*)(grow + c);
;                             stq(orow + c, b + (g * gs) * acc[ai][bj][m][n]); }
;                     asm volatile("" ::: "memory"); }
.LBB0_312:
	s_sub_u32 s36, s54, 0x8000000
	s_subb_u32 s37, s55, 0
	s_add_u32 s38, s56, 0x8000
	s_addc_u32 s39, s57, 0
	v_lshlrev_b32_e32 v3, 2, v2
	v_lshlrev_b32_e32 v16, 1, v2
	v_lshl_add_u32 v16, v18, 13, v16
	v_mov_b32_e32 v19, v16
	v_lshlrev_b32_e32 v19, 1, v19
	global_load_dwordx4 v[204:207], v19, s[36:37]
	global_load_dwordx4 v[208:211], v19, s[36:37] offset:64
	global_load_dwordx4 v[212:215], v19, s[36:37] offset:512
	global_load_dwordx4 v[216:219], v19, s[36:37] offset:576
	v_add_u32_e32 v17, 0xffffe000, v18
	v_ashrrev_i32_e32 v17, 3, v17
	v_add_u32_e32 v17, 1, v17
	v_max_i32_e32 v17, 0, v17
	v_mad_u32_u24 v17, v17, s0, v3
	global_load_dwordx4 v[220:223], v17, s[38:39]
	global_load_dwordx4 v[224:227], v17, s[38:39] offset:64
	global_load_dwordx4 v[228:231], v17, s[38:39] offset:512
	global_load_dwordx4 v[232:235], v17, s[38:39] offset:576
	v_add_u32_e32 v19, 0x20000, v16
	v_lshlrev_b32_e32 v19, 1, v19
	global_load_dwordx4 v[236:239], v19, s[36:37]
	global_load_dwordx4 v[240:243], v19, s[36:37] offset:64
	global_load_dwordx4 v[244:247], v19, s[36:37] offset:512
	global_load_dwordx4 v[248:251], v19, s[36:37] offset:576
	v_add_u32_e32 v17, 0xffffe010, v18
	v_ashrrev_i32_e32 v17, 3, v17
	v_add_u32_e32 v17, 1, v17
	v_max_i32_e32 v17, 0, v17
	v_mad_u32_u24 v17, v17, s0, v3
	global_load_dwordx4 v[192:195], v17, s[38:39]
	global_load_dwordx4 v[184:187], v17, s[38:39] offset:64
	global_load_dwordx4 v[4:7], v17, s[38:39] offset:512
	global_load_dwordx4 v[8:11], v17, s[38:39] offset:576
	s_waitcnt vmcnt(8)
	v_mov_b32_e32 v20, v16
	v_pk_mul_f32 v[220:221], v[220:221], s[20:21] op_sel_hi:[1,0]
	v_pk_mul_f32 v[222:223], v[222:223], s[20:21] op_sel_hi:[1,0]
	v_pk_fma_f32 v[204:205], v[220:221], v[158:159], v[204:205]
	v_pk_fma_f32 v[206:207], v[222:223], v[160:161], v[206:207]
	v_cvt_pk_bf16_f32 v22, v204, v205
	v_cvt_pk_bf16_f32 v23, v206, v207
	global_store_dwordx2 v20, v[22:23], s[68:69]
	v_pk_mul_f32 v[224:225], v[224:225], s[20:21] op_sel_hi:[1,0]
	v_pk_mul_f32 v[226:227], v[226:227], s[20:21] op_sel_hi:[1,0]
	v_pk_fma_f32 v[208:209], v[224:225], v[154:155], v[208:209]
	v_pk_fma_f32 v[210:211], v[226:227], v[156:157], v[210:211]
	v_cvt_pk_bf16_f32 v22, v208, v209
	v_cvt_pk_bf16_f32 v23, v210, v211
	global_store_dwordx2 v20, v[22:23], s[68:69] offset:32
	v_pk_mul_f32 v[228:229], v[228:229], s[20:21] op_sel_hi:[1,0]
	v_pk_mul_f32 v[230:231], v[230:231], s[20:21] op_sel_hi:[1,0]
	v_pk_fma_f32 v[212:213], v[228:229], v[150:151], v[212:213]
	v_pk_fma_f32 v[214:215], v[230:231], v[152:153], v[214:215]
	v_cvt_pk_bf16_f32 v22, v212, v213
	v_cvt_pk_bf16_f32 v23, v214, v215
	global_store_dwordx2 v20, v[22:23], s[68:69] offset:256
	v_pk_mul_f32 v[232:233], v[232:233], s[20:21] op_sel_hi:[1,0]
	v_pk_mul_f32 v[234:235], v[234:235], s[20:21] op_sel_hi:[1,0]
	v_pk_fma_f32 v[216:217], v[232:233], v[146:147], v[216:217]
	v_pk_fma_f32 v[218:219], v[234:235], v[148:149], v[218:219]
	v_cvt_pk_bf16_f32 v22, v216, v217
	v_cvt_pk_bf16_f32 v23, v218, v219
	global_store_dwordx2 v20, v[22:23], s[68:69] offset:288
	v_add_u32_e32 v19, 0x40000, v16
	v_lshlrev_b32_e32 v19, 1, v19
	global_load_dwordx4 v[204:207], v19, s[36:37]
	global_load_dwordx4 v[208:211], v19, s[36:37] offset:64
	global_load_dwordx4 v[212:215], v19, s[36:37] offset:512
	global_load_dwordx4 v[216:219], v19, s[36:37] offset:576
	v_add_u32_e32 v17, 0xffffe020, v18
	v_ashrrev_i32_e32 v17, 3, v17
	v_add_u32_e32 v17, 1, v17
	v_max_i32_e32 v17, 0, v17
	v_mad_u32_u24 v17, v17, s0, v3
	global_load_dwordx4 v[220:223], v17, s[38:39]
	global_load_dwordx4 v[224:227], v17, s[38:39] offset:64
	global_load_dwordx4 v[228:231], v17, s[38:39] offset:512
	global_load_dwordx4 v[232:235], v17, s[38:39] offset:576
	s_waitcnt vmcnt(12)
	v_add_u32_e32 v20, 0x20000, v16
	v_pk_mul_f32 v[192:193], v[192:193], s[20:21] op_sel_hi:[1,0]
	v_pk_mul_f32 v[194:195], v[194:195], s[20:21] op_sel_hi:[1,0]
	v_pk_fma_f32 v[236:237], v[192:193], v[142:143], v[236:237]
	v_pk_fma_f32 v[238:239], v[194:195], v[144:145], v[238:239]
	v_cvt_pk_bf16_f32 v22, v236, v237
	v_cvt_pk_bf16_f32 v23, v238, v239
	global_store_dwordx2 v20, v[22:23], s[68:69]
	v_pk_mul_f32 v[184:185], v[184:185], s[20:21] op_sel_hi:[1,0]
	v_pk_mul_f32 v[186:187], v[186:187], s[20:21] op_sel_hi:[1,0]
	v_pk_fma_f32 v[240:241], v[184:185], v[138:139], v[240:241]
	v_pk_fma_f32 v[242:243], v[186:187], v[140:141], v[242:243]
	v_cvt_pk_bf16_f32 v22, v240, v241
	v_cvt_pk_bf16_f32 v23, v242, v243
	global_store_dwordx2 v20, v[22:23], s[68:69] offset:32
	v_pk_mul_f32 v[4:5], v[4:5], s[20:21] op_sel_hi:[1,0]
	v_pk_mul_f32 v[6:7], v[6:7], s[20:21] op_sel_hi:[1,0]
	v_pk_fma_f32 v[244:245], v[4:5], v[134:135], v[244:245]
	v_pk_fma_f32 v[246:247], v[6:7], v[136:137], v[246:247]
	v_cvt_pk_bf16_f32 v22, v244, v245
	v_cvt_pk_bf16_f32 v23, v246, v247
	global_store_dwordx2 v20, v[22:23], s[68:69] offset:256
	v_pk_mul_f32 v[8:9], v[8:9], s[20:21] op_sel_hi:[1,0]
	v_pk_mul_f32 v[10:11], v[10:11], s[20:21] op_sel_hi:[1,0]
	v_pk_fma_f32 v[248:249], v[8:9], v[130:131], v[248:249]
	v_pk_fma_f32 v[250:251], v[10:11], v[132:133], v[250:251]
	v_cvt_pk_bf16_f32 v22, v248, v249
	v_cvt_pk_bf16_f32 v23, v250, v251
	global_store_dwordx2 v20, v[22:23], s[68:69] offset:288
	v_add_u32_e32 v19, 0x60000, v16
	v_lshlrev_b32_e32 v19, 1, v19
	global_load_dwordx4 v[236:239], v19, s[36:37]
	global_load_dwordx4 v[240:243], v19, s[36:37] offset:64
	global_load_dwordx4 v[244:247], v19, s[36:37] offset:512
	global_load_dwordx4 v[248:251], v19, s[36:37] offset:576
	v_add_u32_e32 v17, 0xffffe030, v18
	v_ashrrev_i32_e32 v17, 3, v17
	v_add_u32_e32 v17, 1, v17
	v_max_i32_e32 v17, 0, v17
	v_mad_u32_u24 v17, v17, s0, v3
	global_load_dwordx4 v[192:195], v17, s[38:39]
	global_load_dwordx4 v[184:187], v17, s[38:39] offset:64
	global_load_dwordx4 v[4:7], v17, s[38:39] offset:512
	global_load_dwordx4 v[8:11], v17, s[38:39] offset:576
	s_waitcnt vmcnt(12)
;     static __device__ __forceinline__ const void* rowptr(const void* b, size_t r, int ldc) { if constexpr (BASE_BF16) return (const bf16_t*)b + r * ldc; else return (const float*)b + r * ldc; }
;     static __device__ __forceinline__ void stq(bf16_t* p, f32x4 v) { u32x2 w; w.x = cvt_pk_bf16(v[0], v[1]); w.y = cvt_pk_bf16(v[2], v[3]); *(u32x2*)p = w; }
;     __device__ __forceinline__ void operator()(const f32x4 (&acc)[2][2][4][2], const Unit& u, int wr, int wc, int fr, int fq) const {
;     ...
;             for (int ai = 0; ai < 2; ++ai)
; #pragma unroll
;                 for (int m = 0; m < 4; ++m) { const int r = u.pm * BM + ai * HALF + wr * 64 + m * 16 + fr;
;                     const void* brow = (r < split_rows) ? rowptr(base_p, (size_t)r, ldc) : rowptr(base_s, (size_t)(r - split_rows), ldc);
;                     const float* grow = mod + (size_t)((r < split_rows) ? 0 : 1 + ((r - split_rows) >> 3)) * modld + goff;
;                     bf16_t* orow = out + (size_t)r * ldc;
; #pragma unroll
;                     for (int bj = 0; bj < 2; ++bj)
; #pragma unroll
;                         for (int n = 0; n < 2; ++n) { const int c = col0 + bj * HALF + n * 16;
;                             const f32x4 b = ldb(brow, c), g = *(const f32x4*)(grow + c);
;                             stq(orow + c, b + (g * gs) * acc[ai][bj][m][n]); }
;                     asm volatile("" ::: "memory"); }
	v_add_u32_e32 v20, 0x40000, v16
	v_pk_mul_f32 v[220:221], v[220:221], s[20:21] op_sel_hi:[1,0]
	v_pk_mul_f32 v[222:223], v[222:223], s[20:21] op_sel_hi:[1,0]
	v_pk_fma_f32 v[204:205], v[220:221], v[126:127], v[204:205]
	v_pk_fma_f32 v[206:207], v[222:223], v[128:129], v[206:207]
	v_cvt_pk_bf16_f32 v22, v204, v205
	v_cvt_pk_bf16_f32 v23, v206, v207
	global_store_dwordx2 v20, v[22:23], s[68:69]
	v_pk_mul_f32 v[224:225], v[224:225], s[20:21] op_sel_hi:[1,0]
	v_pk_mul_f32 v[226:227], v[226:227], s[20:21] op_sel_hi:[1,0]
	v_pk_fma_f32 v[208:209], v[224:225], v[122:123], v[208:209]
	v_pk_fma_f32 v[210:211], v[226:227], v[124:125], v[210:211]
	v_cvt_pk_bf16_f32 v22, v208, v209
	v_cvt_pk_bf16_f32 v23, v210, v211
	global_store_dwordx2 v20, v[22:23], s[68:69] offset:32
	v_pk_mul_f32 v[228:229], v[228:229], s[20:21] op_sel_hi:[1,0]
	v_pk_mul_f32 v[230:231], v[230:231], s[20:21] op_sel_hi:[1,0]
	v_pk_fma_f32 v[212:213], v[228:229], v[118:119], v[212:213]
	v_pk_fma_f32 v[214:215], v[230:231], v[120:121], v[214:215]
	v_cvt_pk_bf16_f32 v22, v212, v213
	v_cvt_pk_bf16_f32 v23, v214, v215
	global_store_dwordx2 v20, v[22:23], s[68:69] offset:256
	v_pk_mul_f32 v[232:233], v[232:233], s[20:21] op_sel_hi:[1,0]
	v_pk_mul_f32 v[234:235], v[234:235], s[20:21] op_sel_hi:[1,0]
	v_pk_fma_f32 v[216:217], v[232:233], v[114:115], v[216:217]
	v_pk_fma_f32 v[218:219], v[234:235], v[116:117], v[218:219]
	v_cvt_pk_bf16_f32 v22, v216, v217
	v_cvt_pk_bf16_f32 v23, v218, v219
	global_store_dwordx2 v20, v[22:23], s[68:69] offset:288
	v_add_u32_e32 v19, 0x100000, v16
	v_lshlrev_b32_e32 v19, 1, v19
	global_load_dwordx4 v[204:207], v19, s[36:37]
	global_load_dwordx4 v[208:211], v19, s[36:37] offset:64
	global_load_dwordx4 v[212:215], v19, s[36:37] offset:512
	global_load_dwordx4 v[216:219], v19, s[36:37] offset:576
	v_add_u32_e32 v17, 0xffffe080, v18
	v_ashrrev_i32_e32 v17, 3, v17
	v_add_u32_e32 v17, 1, v17
	v_max_i32_e32 v17, 0, v17
	v_mad_u32_u24 v17, v17, s0, v3
	global_load_dwordx4 v[220:223], v17, s[38:39]
	global_load_dwordx4 v[224:227], v17, s[38:39] offset:64
	global_load_dwordx4 v[228:231], v17, s[38:39] offset:512
	global_load_dwordx4 v[232:235], v17, s[38:39] offset:576
	s_waitcnt vmcnt(12)
	v_add_u32_e32 v20, 0x60000, v16
	v_pk_mul_f32 v[192:193], v[192:193], s[20:21] op_sel_hi:[1,0]
	v_pk_mul_f32 v[194:195], v[194:195], s[20:21] op_sel_hi:[1,0]
	v_pk_fma_f32 v[236:237], v[192:193], v[110:111], v[236:237]
	v_pk_fma_f32 v[238:239], v[194:195], v[112:113], v[238:239]
	v_cvt_pk_bf16_f32 v22, v236, v237
	v_cvt_pk_bf16_f32 v23, v238, v239
	global_store_dwordx2 v20, v[22:23], s[68:69]
	v_pk_mul_f32 v[184:185], v[184:185], s[20:21] op_sel_hi:[1,0]
	v_pk_mul_f32 v[186:187], v[186:187], s[20:21] op_sel_hi:[1,0]
	v_pk_fma_f32 v[240:241], v[184:185], v[106:107], v[240:241]
	v_pk_fma_f32 v[242:243], v[186:187], v[108:109], v[242:243]
	v_cvt_pk_bf16_f32 v22, v240, v241
	v_cvt_pk_bf16_f32 v23, v242, v243
	global_store_dwordx2 v20, v[22:23], s[68:69] offset:32
	v_pk_mul_f32 v[4:5], v[4:5], s[20:21] op_sel_hi:[1,0]
	v_pk_mul_f32 v[6:7], v[6:7], s[20:21] op_sel_hi:[1,0]
	v_pk_fma_f32 v[244:245], v[4:5], v[102:103], v[244:245]
	v_pk_fma_f32 v[246:247], v[6:7], v[104:105], v[246:247]
	v_cvt_pk_bf16_f32 v22, v244, v245
	v_cvt_pk_bf16_f32 v23, v246, v247
	global_store_dwordx2 v20, v[22:23], s[68:69] offset:256
	v_pk_mul_f32 v[8:9], v[8:9], s[20:21] op_sel_hi:[1,0]
	v_pk_mul_f32 v[10:11], v[10:11], s[20:21] op_sel_hi:[1,0]
	v_pk_fma_f32 v[248:249], v[8:9], v[98:99], v[248:249]
	v_pk_fma_f32 v[250:251], v[10:11], v[100:101], v[250:251]
	v_cvt_pk_bf16_f32 v22, v248, v249
	v_cvt_pk_bf16_f32 v23, v250, v251
	global_store_dwordx2 v20, v[22:23], s[68:69] offset:288
	v_add_u32_e32 v19, 0x120000, v16
	v_lshlrev_b32_e32 v19, 1, v19
	global_load_dwordx4 v[236:239], v19, s[36:37]
	global_load_dwordx4 v[240:243], v19, s[36:37] offset:64
	global_load_dwordx4 v[244:247], v19, s[36:37] offset:512
	global_load_dwordx4 v[248:251], v19, s[36:37] offset:576
	v_add_u32_e32 v17, 0xffffe090, v18
	v_ashrrev_i32_e32 v17, 3, v17
	v_add_u32_e32 v17, 1, v17
	v_max_i32_e32 v17, 0, v17
	v_mad_u32_u24 v17, v17, s0, v3
	global_load_dwordx4 v[192:195], v17, s[38:39]
	global_load_dwordx4 v[184:187], v17, s[38:39] offset:64
	global_load_dwordx4 v[4:7], v17, s[38:39] offset:512
	global_load_dwordx4 v[8:11], v17, s[38:39] offset:576
	s_waitcnt vmcnt(12)
	v_add_u32_e32 v20, 0x100000, v16
	v_pk_mul_f32 v[220:221], v[220:221], s[20:21] op_sel_hi:[1,0]
	v_pk_mul_f32 v[222:223], v[222:223], s[20:21] op_sel_hi:[1,0]
	v_pk_fma_f32 v[204:205], v[220:221], v[94:95], v[204:205]
	v_pk_fma_f32 v[206:207], v[222:223], v[96:97], v[206:207]
	v_cvt_pk_bf16_f32 v22, v204, v205
	v_cvt_pk_bf16_f32 v23, v206, v207
	global_store_dwordx2 v20, v[22:23], s[68:69]
	v_pk_mul_f32 v[224:225], v[224:225], s[20:21] op_sel_hi:[1,0]
	v_pk_mul_f32 v[226:227], v[226:227], s[20:21] op_sel_hi:[1,0]
	v_pk_fma_f32 v[208:209], v[224:225], v[90:91], v[208:209]
	v_pk_fma_f32 v[210:211], v[226:227], v[92:93], v[210:211]
	v_cvt_pk_bf16_f32 v22, v208, v209
	v_cvt_pk_bf16_f32 v23, v210, v211
	global_store_dwordx2 v20, v[22:23], s[68:69] offset:32
	v_pk_mul_f32 v[228:229], v[228:229], s[20:21] op_sel_hi:[1,0]
	v_pk_mul_f32 v[230:231], v[230:231], s[20:21] op_sel_hi:[1,0]
	v_pk_fma_f32 v[212:213], v[228:229], v[86:87], v[212:213]
	v_pk_fma_f32 v[214:215], v[230:231], v[88:89], v[214:215]
	v_cvt_pk_bf16_f32 v22, v212, v213
	v_cvt_pk_bf16_f32 v23, v214, v215
	global_store_dwordx2 v20, v[22:23], s[68:69] offset:256
	v_pk_mul_f32 v[232:233], v[232:233], s[20:21] op_sel_hi:[1,0]
	v_pk_mul_f32 v[234:235], v[234:235], s[20:21] op_sel_hi:[1,0]
	v_pk_fma_f32 v[216:217], v[232:233], v[82:83], v[216:217]
	v_pk_fma_f32 v[218:219], v[234:235], v[84:85], v[218:219]
	v_cvt_pk_bf16_f32 v22, v216, v217
	v_cvt_pk_bf16_f32 v23, v218, v219
	global_store_dwordx2 v20, v[22:23], s[68:69] offset:288
	v_add_u32_e32 v19, 0x140000, v16
	v_lshlrev_b32_e32 v19, 1, v19
	global_load_dwordx4 v[204:207], v19, s[36:37]
	global_load_dwordx4 v[208:211], v19, s[36:37] offset:64
	global_load_dwordx4 v[212:215], v19, s[36:37] offset:512
	global_load_dwordx4 v[216:219], v19, s[36:37] offset:576
	v_add_u32_e32 v17, 0xffffe0a0, v18
	v_ashrrev_i32_e32 v17, 3, v17
	v_add_u32_e32 v17, 1, v17
	v_max_i32_e32 v17, 0, v17
	v_mad_u32_u24 v17, v17, s0, v3
	global_load_dwordx4 v[220:223], v17, s[38:39]
	global_load_dwordx4 v[224:227], v17, s[38:39] offset:64
	global_load_dwordx4 v[228:231], v17, s[38:39] offset:512
	global_load_dwordx4 v[232:235], v17, s[38:39] offset:576
	s_waitcnt vmcnt(12)
;     static __device__ __forceinline__ const void* rowptr(const void* b, size_t r, int ldc) { if constexpr (BASE_BF16) return (const bf16_t*)b + r * ldc; else return (const float*)b + r * ldc; }
;     static __device__ __forceinline__ void stq(bf16_t* p, f32x4 v) { u32x2 w; w.x = cvt_pk_bf16(v[0], v[1]); w.y = cvt_pk_bf16(v[2], v[3]); *(u32x2*)p = w; }
;     __device__ __forceinline__ void operator()(const f32x4 (&acc)[2][2][4][2], const Unit& u, int wr, int wc, int fr, int fq) const {
;     ...
;             for (int ai = 0; ai < 2; ++ai)
; #pragma unroll
;                 for (int m = 0; m < 4; ++m) { const int r = u.pm * BM + ai * HALF + wr * 64 + m * 16 + fr;
;                     const void* brow = (r < split_rows) ? rowptr(base_p, (size_t)r, ldc) : rowptr(base_s, (size_t)(r - split_rows), ldc);
;                     const float* grow = mod + (size_t)((r < split_rows) ? 0 : 1 + ((r - split_rows) >> 3)) * modld + goff;
;                     bf16_t* orow = out + (size_t)r * ldc;
; #pragma unroll
;                     for (int bj = 0; bj < 2; ++bj)
; #pragma unroll
;                         for (int n = 0; n < 2; ++n) { const int c = col0 + bj * HALF + n * 16;
;                             const f32x4 b = ldb(brow, c), g = *(const f32x4*)(grow + c);
;                             stq(orow + c, b + (g * gs) * acc[ai][bj][m][n]); }
;                     asm volatile("" ::: "memory"); }
	v_add_u32_e32 v20, 0x120000, v16
	v_pk_mul_f32 v[192:193], v[192:193], s[20:21] op_sel_hi:[1,0]
	v_pk_mul_f32 v[194:195], v[194:195], s[20:21] op_sel_hi:[1,0]
	v_pk_fma_f32 v[236:237], v[192:193], v[78:79], v[236:237]
	v_pk_fma_f32 v[238:239], v[194:195], v[80:81], v[238:239]
	v_cvt_pk_bf16_f32 v22, v236, v237
	v_cvt_pk_bf16_f32 v23, v238, v239
	global_store_dwordx2 v20, v[22:23], s[68:69]
	v_pk_mul_f32 v[184:185], v[184:185], s[20:21] op_sel_hi:[1,0]
	v_pk_mul_f32 v[186:187], v[186:187], s[20:21] op_sel_hi:[1,0]
	v_pk_fma_f32 v[240:241], v[184:185], v[74:75], v[240:241]
	v_pk_fma_f32 v[242:243], v[186:187], v[76:77], v[242:243]
	v_cvt_pk_bf16_f32 v22, v240, v241
	v_cvt_pk_bf16_f32 v23, v242, v243
	global_store_dwordx2 v20, v[22:23], s[68:69] offset:32
	v_pk_mul_f32 v[4:5], v[4:5], s[20:21] op_sel_hi:[1,0]
	v_pk_mul_f32 v[6:7], v[6:7], s[20:21] op_sel_hi:[1,0]
	v_pk_fma_f32 v[244:245], v[4:5], v[70:71], v[244:245]
	v_pk_fma_f32 v[246:247], v[6:7], v[72:73], v[246:247]
	v_cvt_pk_bf16_f32 v22, v244, v245
	v_cvt_pk_bf16_f32 v23, v246, v247
	global_store_dwordx2 v20, v[22:23], s[68:69] offset:256
	v_pk_mul_f32 v[8:9], v[8:9], s[20:21] op_sel_hi:[1,0]
	v_pk_mul_f32 v[10:11], v[10:11], s[20:21] op_sel_hi:[1,0]
	v_pk_fma_f32 v[248:249], v[8:9], v[66:67], v[248:249]
	v_pk_fma_f32 v[250:251], v[10:11], v[68:69], v[250:251]
	v_cvt_pk_bf16_f32 v22, v248, v249
	v_cvt_pk_bf16_f32 v23, v250, v251
	global_store_dwordx2 v20, v[22:23], s[68:69] offset:288
	v_add_u32_e32 v19, 0x160000, v16
	v_lshlrev_b32_e32 v19, 1, v19
	global_load_dwordx4 v[236:239], v19, s[36:37]
	global_load_dwordx4 v[240:243], v19, s[36:37] offset:64
	global_load_dwordx4 v[244:247], v19, s[36:37] offset:512
	global_load_dwordx4 v[248:251], v19, s[36:37] offset:576
	v_add_u32_e32 v17, 0xffffe0b0, v18
	v_ashrrev_i32_e32 v17, 3, v17
	v_add_u32_e32 v17, 1, v17
	v_max_i32_e32 v17, 0, v17
	v_mad_u32_u24 v17, v17, s0, v3
	global_load_dwordx4 v[192:195], v17, s[38:39]
	global_load_dwordx4 v[184:187], v17, s[38:39] offset:64
	global_load_dwordx4 v[4:7], v17, s[38:39] offset:512
	global_load_dwordx4 v[8:11], v17, s[38:39] offset:576
	s_waitcnt vmcnt(12)
	v_add_u32_e32 v20, 0x140000, v16
	v_pk_mul_f32 v[220:221], v[220:221], s[20:21] op_sel_hi:[1,0]
	v_pk_mul_f32 v[222:223], v[222:223], s[20:21] op_sel_hi:[1,0]
	v_pk_fma_f32 v[204:205], v[220:221], v[62:63], v[204:205]
	v_pk_fma_f32 v[206:207], v[222:223], v[64:65], v[206:207]
	v_cvt_pk_bf16_f32 v22, v204, v205
	v_cvt_pk_bf16_f32 v23, v206, v207
	global_store_dwordx2 v20, v[22:23], s[68:69]
	v_pk_mul_f32 v[224:225], v[224:225], s[20:21] op_sel_hi:[1,0]
	v_pk_mul_f32 v[226:227], v[226:227], s[20:21] op_sel_hi:[1,0]
	v_pk_fma_f32 v[208:209], v[224:225], v[58:59], v[208:209]
	v_pk_fma_f32 v[210:211], v[226:227], v[60:61], v[210:211]
	v_cvt_pk_bf16_f32 v22, v208, v209
	v_cvt_pk_bf16_f32 v23, v210, v211
	global_store_dwordx2 v20, v[22:23], s[68:69] offset:32
	v_pk_mul_f32 v[228:229], v[228:229], s[20:21] op_sel_hi:[1,0]
	v_pk_mul_f32 v[230:231], v[230:231], s[20:21] op_sel_hi:[1,0]
	v_pk_fma_f32 v[212:213], v[228:229], v[54:55], v[212:213]
	v_pk_fma_f32 v[214:215], v[230:231], v[56:57], v[214:215]
	v_cvt_pk_bf16_f32 v22, v212, v213
	v_cvt_pk_bf16_f32 v23, v214, v215
	global_store_dwordx2 v20, v[22:23], s[68:69] offset:256
	v_pk_mul_f32 v[232:233], v[232:233], s[20:21] op_sel_hi:[1,0]
	v_pk_mul_f32 v[234:235], v[234:235], s[20:21] op_sel_hi:[1,0]
	v_pk_fma_f32 v[216:217], v[232:233], v[50:51], v[216:217]
	v_pk_fma_f32 v[218:219], v[234:235], v[52:53], v[218:219]
	v_cvt_pk_bf16_f32 v22, v216, v217
	v_cvt_pk_bf16_f32 v23, v218, v219
	global_store_dwordx2 v20, v[22:23], s[68:69] offset:288
	s_waitcnt vmcnt(4)
	v_add_u32_e32 v20, 0x160000, v16
	v_pk_mul_f32 v[192:193], v[192:193], s[20:21] op_sel_hi:[1,0]
	v_pk_mul_f32 v[194:195], v[194:195], s[20:21] op_sel_hi:[1,0]
	v_pk_fma_f32 v[236:237], v[192:193], v[46:47], v[236:237]
	v_pk_fma_f32 v[238:239], v[194:195], v[48:49], v[238:239]
	v_cvt_pk_bf16_f32 v22, v236, v237
	v_cvt_pk_bf16_f32 v23, v238, v239
	global_store_dwordx2 v20, v[22:23], s[68:69]
	v_pk_mul_f32 v[184:185], v[184:185], s[20:21] op_sel_hi:[1,0]
	v_pk_mul_f32 v[186:187], v[186:187], s[20:21] op_sel_hi:[1,0]
	v_pk_fma_f32 v[240:241], v[184:185], v[42:43], v[240:241]
	v_pk_fma_f32 v[242:243], v[186:187], v[44:45], v[242:243]
	v_cvt_pk_bf16_f32 v22, v240, v241
	v_cvt_pk_bf16_f32 v23, v242, v243
	global_store_dwordx2 v20, v[22:23], s[68:69] offset:32
	v_pk_mul_f32 v[4:5], v[4:5], s[20:21] op_sel_hi:[1,0]
	v_pk_mul_f32 v[6:7], v[6:7], s[20:21] op_sel_hi:[1,0]
	v_pk_fma_f32 v[244:245], v[4:5], v[38:39], v[244:245]
	v_pk_fma_f32 v[246:247], v[6:7], v[40:41], v[246:247]
	v_cvt_pk_bf16_f32 v22, v244, v245
	v_cvt_pk_bf16_f32 v23, v246, v247
	global_store_dwordx2 v20, v[22:23], s[68:69] offset:256
	v_pk_mul_f32 v[8:9], v[8:9], s[20:21] op_sel_hi:[1,0]
	v_pk_mul_f32 v[10:11], v[10:11], s[20:21] op_sel_hi:[1,0]
	v_pk_fma_f32 v[248:249], v[8:9], v[34:35], v[248:249]
	v_pk_fma_f32 v[250:251], v[10:11], v[36:37], v[250:251]
	v_cvt_pk_bf16_f32 v22, v248, v249
	v_cvt_pk_bf16_f32 v23, v250, v251
	global_store_dwordx2 v20, v[22:23], s[68:69] offset:288
	s_branch .LBB0_311

;     static __device__ __forceinline__ const void* rowptr(const void* b, size_t r, int ldc) { if constexpr (BASE_BF16) return (const bf16_t*)b + r * ldc; else return (const float*)b + r * ldc; }
;     static __device__ __forceinline__ void stq(bf16_t* p, f32x4 v) { u32x2 w; w.x = cvt_pk_bf16(v[0], v[1]); w.y = cvt_pk_bf16(v[2], v[3]); *(u32x2*)p = w; }
;     __device__ __forceinline__ void operator()(const f32x4 (&acc)[2][2][4][2], const Unit& u, int wr, int wc, int fr, int fq) const {
;     ...
;             for (int ai = 0; ai < 2; ++ai)
; #pragma unroll
;                 for (int m = 0; m < 4; ++m) { const int r = u.pm * BM + ai * HALF + wr * 64 + m * 16 + fr;
;                     const void* brow = (r < split_rows) ? rowptr(base_p, (size_t)r, ldc) : rowptr(base_s, (size_t)(r - split_rows), ldc);
;                     const float* grow = mod + (size_t)((r < split_rows) ? 0 : 1 + ((r - split_rows) >> 3)) * modld + goff;
;                     bf16_t* orow = out + (size_t)r * ldc;
; #pragma unroll
;                     for (int bj = 0; bj < 2; ++bj)
; #pragma unroll
;                         for (int n = 0; n < 2; ++n) { const int c = col0 + bj * HALF + n * 16;
;                             const f32x4 b = ldb(brow, c), g = *(const f32x4*)(grow + c);
;                             stq(orow + c, b + (g * gs) * acc[ai][bj][m][n]); }
;                     asm volatile("" ::: "memory"); }
.LBB0_731:
	s_add_u32 s60, s56, s20
	s_addc_u32 s61, s57, s21
	v_lshlrev_b32_e32 v131, 1, v130
	v_lshlrev_b32_e32 v132, 2, v130
	v_lshl_add_u32 v134, v160, 13, v131
	v_add_u32_e32 v133, 0xffffe000, v160
	v_ashrrev_i32_e32 v133, 3, v133
	v_add_u32_e32 v133, 1, v133
	v_max_i32_e32 v133, 0, v133
	v_mad_u32_u24 v180, v133, s81, v132
	v_add_u32_e32 v135, 0x20000, v134
	v_add_u32_e32 v133, 0xffffe010, v160
	v_ashrrev_i32_e32 v133, 3, v133
	v_add_u32_e32 v133, 1, v133
	v_max_i32_e32 v133, 0, v133
	v_mad_u32_u24 v181, v133, s81, v132
	v_add_u32_e32 v136, 0x40000, v134
	v_add_u32_e32 v133, 0xffffe020, v160
	v_ashrrev_i32_e32 v133, 3, v133
	v_add_u32_e32 v133, 1, v133
	v_max_i32_e32 v133, 0, v133
	v_mad_u32_u24 v182, v133, s81, v132
	v_add_u32_e32 v137, 0x60000, v134
	v_add_u32_e32 v133, 0xffffe030, v160
	v_ashrrev_i32_e32 v133, 3, v133
	v_add_u32_e32 v133, 1, v133
	v_max_i32_e32 v133, 0, v133
	v_mad_u32_u24 v183, v133, s81, v132
	v_add_u32_e32 v138, 0x100000, v134
	v_add_u32_e32 v133, 0xffffe080, v160
	v_ashrrev_i32_e32 v133, 3, v133
	v_add_u32_e32 v133, 1, v133
	v_max_i32_e32 v133, 0, v133
	v_mad_u32_u24 v184, v133, s81, v132
	v_add_u32_e32 v139, 0x120000, v134
	v_add_u32_e32 v133, 0xffffe090, v160
	v_ashrrev_i32_e32 v133, 3, v133
	v_add_u32_e32 v133, 1, v133
	v_max_i32_e32 v133, 0, v133
	v_mad_u32_u24 v185, v133, s81, v132
	v_add_u32_e32 v140, 0x140000, v134
	v_add_u32_e32 v133, 0xffffe0a0, v160
	v_ashrrev_i32_e32 v133, 3, v133
	v_add_u32_e32 v133, 1, v133
	v_max_i32_e32 v133, 0, v133
	v_mad_u32_u24 v186, v133, s81, v132
	v_add_u32_e32 v141, 0x160000, v134
	v_add_u32_e32 v133, 0xffffe0b0, v160
	v_ashrrev_i32_e32 v133, 3, v133
	v_add_u32_e32 v133, 1, v133
	v_max_i32_e32 v133, 0, v133
	v_mad_u32_u24 v187, v133, s81, v132
	global_load_dwordx2 v[190:191], v134, s[68:69]
	global_load_dwordx2 v[192:193], v134, s[68:69] offset:32
	global_load_dwordx2 v[194:195], v134, s[68:69] offset:256
	global_load_dwordx2 v[196:197], v134, s[68:69] offset:288
	global_load_dwordx4 v[198:201], v180, s[60:61]
	global_load_dwordx4 v[202:205], v180, s[60:61] offset:64
	global_load_dwordx4 v[206:209], v180, s[60:61] offset:512
	global_load_dwordx4 v[210:213], v180, s[60:61] offset:576
	global_load_dwordx2 v[214:215], v135, s[68:69]
	global_load_dwordx2 v[216:217], v135, s[68:69] offset:32
	global_load_dwordx2 v[218:219], v135, s[68:69] offset:256
	global_load_dwordx2 v[220:221], v135, s[68:69] offset:288
	global_load_dwordx4 v[222:225], v181, s[60:61]
	global_load_dwordx4 v[226:229], v181, s[60:61] offset:64
	global_load_dwordx4 v[230:233], v181, s[60:61] offset:512
	global_load_dwordx4 v[234:237], v181, s[60:61] offset:576
	s_waitcnt vmcnt(8)
	v_lshlrev_b32_e32 v142, 16, v190
	v_and_b32_e32 v143, 0xffff0000, v190
	v_lshlrev_b32_e32 v144, 16, v191
	v_and_b32_e32 v145, 0xffff0000, v191
	v_pk_fma_f32 v[142:143], v[198:199], v[126:127], v[142:143]
	v_pk_fma_f32 v[144:145], v[200:201], v[128:129], v[144:145]
	v_cvt_pk_bf16_f32 v188, v142, v143
	v_cvt_pk_bf16_f32 v189, v144, v145
	global_store_dwordx2 v134, v[188:189], s[68:69]
	v_lshlrev_b32_e32 v142, 16, v192
	v_and_b32_e32 v143, 0xffff0000, v192
	v_lshlrev_b32_e32 v144, 16, v193
	v_and_b32_e32 v145, 0xffff0000, v193
	v_pk_fma_f32 v[142:143], v[202:203], v[122:123], v[142:143]
	v_pk_fma_f32 v[144:145], v[204:205], v[124:125], v[144:145]
	v_cvt_pk_bf16_f32 v188, v142, v143
	v_cvt_pk_bf16_f32 v189, v144, v145
	global_store_dwordx2 v134, v[188:189], s[68:69] offset:32
	v_lshlrev_b32_e32 v142, 16, v194
	v_and_b32_e32 v143, 0xffff0000, v194
	v_lshlrev_b32_e32 v144, 16, v195
	v_and_b32_e32 v145, 0xffff0000, v195
	v_pk_fma_f32 v[142:143], v[206:207], v[118:119], v[142:143]
	v_pk_fma_f32 v[144:145], v[208:209], v[120:121], v[144:145]
	v_cvt_pk_bf16_f32 v188, v142, v143
	v_cvt_pk_bf16_f32 v189, v144, v145
	global_store_dwordx2 v134, v[188:189], s[68:69] offset:256
	v_lshlrev_b32_e32 v142, 16, v196
	v_and_b32_e32 v143, 0xffff0000, v196
	v_lshlrev_b32_e32 v144, 16, v197
	v_and_b32_e32 v145, 0xffff0000, v197
	v_pk_fma_f32 v[142:143], v[210:211], v[114:115], v[142:143]
	v_pk_fma_f32 v[144:145], v[212:213], v[116:117], v[144:145]
	v_cvt_pk_bf16_f32 v188, v142, v143
	v_cvt_pk_bf16_f32 v189, v144, v145
	global_store_dwordx2 v134, v[188:189], s[68:69] offset:288
	global_load_dwordx2 v[190:191], v136, s[68:69]
	global_load_dwordx2 v[192:193], v136, s[68:69] offset:32
	global_load_dwordx2 v[194:195], v136, s[68:69] offset:256
	global_load_dwordx2 v[196:197], v136, s[68:69] offset:288
	global_load_dwordx4 v[198:201], v182, s[60:61]
	global_load_dwordx4 v[202:205], v182, s[60:61] offset:64
	global_load_dwordx4 v[206:209], v182, s[60:61] offset:512
	global_load_dwordx4 v[210:213], v182, s[60:61] offset:576
	s_waitcnt vmcnt(12)
;     static __device__ __forceinline__ const void* rowptr(const void* b, size_t r, int ldc) { if constexpr (BASE_BF16) return (const bf16_t*)b + r * ldc; else return (const float*)b + r * ldc; }
;     static __device__ __forceinline__ void stq(bf16_t* p, f32x4 v) { u32x2 w; w.x = cvt_pk_bf16(v[0], v[1]); w.y = cvt_pk_bf16(v[2], v[3]); *(u32x2*)p = w; }
;     __device__ __forceinline__ void operator()(const f32x4 (&acc)[2][2][4][2], const Unit& u, int wr, int wc, int fr, int fq) const {
;     ...
;             for (int ai = 0; ai < 2; ++ai)
; #pragma unroll
;                 for (int m = 0; m < 4; ++m) { const int r = u.pm * BM + ai * HALF + wr * 64 + m * 16 + fr;
;                     const void* brow = (r < split_rows) ? rowptr(base_p, (size_t)r, ldc) : rowptr(base_s, (size_t)(r - split_rows), ldc);
;                     const float* grow = mod + (size_t)((r < split_rows) ? 0 : 1 + ((r - split_rows) >> 3)) * modld + goff;
;                     bf16_t* orow = out + (size_t)r * ldc;
; #pragma unroll
;                     for (int bj = 0; bj < 2; ++bj)
; #pragma unroll
;                         for (int n = 0; n < 2; ++n) { const int c = col0 + bj * HALF + n * 16;
;                             const f32x4 b = ldb(brow, c), g = *(const f32x4*)(grow + c);
;                             stq(orow + c, b + (g * gs) * acc[ai][bj][m][n]); }
;                     asm volatile("" ::: "memory"); }
	v_lshlrev_b32_e32 v142, 16, v214
	v_and_b32_e32 v143, 0xffff0000, v214
	v_lshlrev_b32_e32 v144, 16, v215
	v_and_b32_e32 v145, 0xffff0000, v215
	v_pk_fma_f32 v[142:143], v[222:223], v[110:111], v[142:143]
	v_pk_fma_f32 v[144:145], v[224:225], v[112:113], v[144:145]
	v_cvt_pk_bf16_f32 v188, v142, v143
	v_cvt_pk_bf16_f32 v189, v144, v145
	global_store_dwordx2 v135, v[188:189], s[68:69]
	v_lshlrev_b32_e32 v142, 16, v216
	v_and_b32_e32 v143, 0xffff0000, v216
	v_lshlrev_b32_e32 v144, 16, v217
	v_and_b32_e32 v145, 0xffff0000, v217
	v_pk_fma_f32 v[142:143], v[226:227], v[106:107], v[142:143]
	v_pk_fma_f32 v[144:145], v[228:229], v[108:109], v[144:145]
	v_cvt_pk_bf16_f32 v188, v142, v143
	v_cvt_pk_bf16_f32 v189, v144, v145
	global_store_dwordx2 v135, v[188:189], s[68:69] offset:32
	v_lshlrev_b32_e32 v142, 16, v218
	v_and_b32_e32 v143, 0xffff0000, v218
	v_lshlrev_b32_e32 v144, 16, v219
	v_and_b32_e32 v145, 0xffff0000, v219
	v_pk_fma_f32 v[142:143], v[230:231], v[102:103], v[142:143]
	v_pk_fma_f32 v[144:145], v[232:233], v[104:105], v[144:145]
	v_cvt_pk_bf16_f32 v188, v142, v143
	v_cvt_pk_bf16_f32 v189, v144, v145
	global_store_dwordx2 v135, v[188:189], s[68:69] offset:256
	v_lshlrev_b32_e32 v142, 16, v220
	v_and_b32_e32 v143, 0xffff0000, v220
	v_lshlrev_b32_e32 v144, 16, v221
	v_and_b32_e32 v145, 0xffff0000, v221
	v_pk_fma_f32 v[142:143], v[234:235], v[98:99], v[142:143]
	v_pk_fma_f32 v[144:145], v[236:237], v[100:101], v[144:145]
	v_cvt_pk_bf16_f32 v188, v142, v143
	v_cvt_pk_bf16_f32 v189, v144, v145
	global_store_dwordx2 v135, v[188:189], s[68:69] offset:288
	global_load_dwordx2 v[214:215], v137, s[68:69]
	global_load_dwordx2 v[216:217], v137, s[68:69] offset:32
	global_load_dwordx2 v[218:219], v137, s[68:69] offset:256
	global_load_dwordx2 v[220:221], v137, s[68:69] offset:288
	global_load_dwordx4 v[222:225], v183, s[60:61]
	global_load_dwordx4 v[226:229], v183, s[60:61] offset:64
	global_load_dwordx4 v[230:233], v183, s[60:61] offset:512
	global_load_dwordx4 v[234:237], v183, s[60:61] offset:576
	s_waitcnt vmcnt(12)
	v_lshlrev_b32_e32 v142, 16, v190
	v_and_b32_e32 v143, 0xffff0000, v190
	v_lshlrev_b32_e32 v144, 16, v191
	v_and_b32_e32 v145, 0xffff0000, v191
	v_pk_fma_f32 v[142:143], v[198:199], v[94:95], v[142:143]
	v_pk_fma_f32 v[144:145], v[200:201], v[96:97], v[144:145]
	v_cvt_pk_bf16_f32 v188, v142, v143
	v_cvt_pk_bf16_f32 v189, v144, v145
	global_store_dwordx2 v136, v[188:189], s[68:69]
	v_lshlrev_b32_e32 v142, 16, v192
	v_and_b32_e32 v143, 0xffff0000, v192
	v_lshlrev_b32_e32 v144, 16, v193
	v_and_b32_e32 v145, 0xffff0000, v193
	v_pk_fma_f32 v[142:143], v[202:203], v[90:91], v[142:143]
	v_pk_fma_f32 v[144:145], v[204:205], v[92:93], v[144:145]
	v_cvt_pk_bf16_f32 v188, v142, v143
	v_cvt_pk_bf16_f32 v189, v144, v145
	global_store_dwordx2 v136, v[188:189], s[68:69] offset:32
	v_lshlrev_b32_e32 v142, 16, v194
	v_and_b32_e32 v143, 0xffff0000, v194
	v_lshlrev_b32_e32 v144, 16, v195
	v_and_b32_e32 v145, 0xffff0000, v195
	v_pk_fma_f32 v[142:143], v[206:207], v[86:87], v[142:143]
	v_pk_fma_f32 v[144:145], v[208:209], v[88:89], v[144:145]
	v_cvt_pk_bf16_f32 v188, v142, v143
	v_cvt_pk_bf16_f32 v189, v144, v145
	global_store_dwordx2 v136, v[188:189], s[68:69] offset:256
	v_lshlrev_b32_e32 v142, 16, v196
	v_and_b32_e32 v143, 0xffff0000, v196
	v_lshlrev_b32_e32 v144, 16, v197
	v_and_b32_e32 v145, 0xffff0000, v197
	v_pk_fma_f32 v[142:143], v[210:211], v[82:83], v[142:143]
	v_pk_fma_f32 v[144:145], v[212:213], v[84:85], v[144:145]
	v_cvt_pk_bf16_f32 v188, v142, v143
	v_cvt_pk_bf16_f32 v189, v144, v145
	global_store_dwordx2 v136, v[188:189], s[68:69] offset:288
	global_load_dwordx2 v[190:191], v138, s[68:69]
	global_load_dwordx2 v[192:193], v138, s[68:69] offset:32
	global_load_dwordx2 v[194:195], v138, s[68:69] offset:256
	global_load_dwordx2 v[196:197], v138, s[68:69] offset:288
	global_load_dwordx4 v[198:201], v184, s[60:61]
	global_load_dwordx4 v[202:205], v184, s[60:61] offset:64
	global_load_dwordx4 v[206:209], v184, s[60:61] offset:512
	global_load_dwordx4 v[210:213], v184, s[60:61] offset:576
	s_waitcnt vmcnt(12)
	v_lshlrev_b32_e32 v142, 16, v214
	v_and_b32_e32 v143, 0xffff0000, v214
	v_lshlrev_b32_e32 v144, 16, v215
	v_and_b32_e32 v145, 0xffff0000, v215
	v_pk_fma_f32 v[142:143], v[222:223], v[78:79], v[142:143]
	v_pk_fma_f32 v[144:145], v[224:225], v[80:81], v[144:145]
	v_cvt_pk_bf16_f32 v188, v142, v143
	v_cvt_pk_bf16_f32 v189, v144, v145
	global_store_dwordx2 v137, v[188:189], s[68:69]
	v_lshlrev_b32_e32 v142, 16, v216
	v_and_b32_e32 v143, 0xffff0000, v216
	v_lshlrev_b32_e32 v144, 16, v217
	v_and_b32_e32 v145, 0xffff0000, v217
	v_pk_fma_f32 v[142:143], v[226:227], v[74:75], v[142:143]
	v_pk_fma_f32 v[144:145], v[228:229], v[76:77], v[144:145]
	v_cvt_pk_bf16_f32 v188, v142, v143
	v_cvt_pk_bf16_f32 v189, v144, v145
	global_store_dwordx2 v137, v[188:189], s[68:69] offset:32
	v_lshlrev_b32_e32 v142, 16, v218
	v_and_b32_e32 v143, 0xffff0000, v218
	v_lshlrev_b32_e32 v144, 16, v219
	v_and_b32_e32 v145, 0xffff0000, v219
	v_pk_fma_f32 v[142:143], v[230:231], v[70:71], v[142:143]
	v_pk_fma_f32 v[144:145], v[232:233], v[72:73], v[144:145]
	v_cvt_pk_bf16_f32 v188, v142, v143
	v_cvt_pk_bf16_f32 v189, v144, v145
	global_store_dwordx2 v137, v[188:189], s[68:69] offset:256
	v_lshlrev_b32_e32 v142, 16, v220
	v_and_b32_e32 v143, 0xffff0000, v220
	v_lshlrev_b32_e32 v144, 16, v221
	v_and_b32_e32 v145, 0xffff0000, v221
	v_pk_fma_f32 v[142:143], v[234:235], v[66:67], v[142:143]
	v_pk_fma_f32 v[144:145], v[236:237], v[68:69], v[144:145]
	v_cvt_pk_bf16_f32 v188, v142, v143
	v_cvt_pk_bf16_f32 v189, v144, v145
	global_store_dwordx2 v137, v[188:189], s[68:69] offset:288
	global_load_dwordx2 v[214:215], v139, s[68:69]
	global_load_dwordx2 v[216:217], v139, s[68:69] offset:32
	global_load_dwordx2 v[218:219], v139, s[68:69] offset:256
	global_load_dwordx2 v[220:221], v139, s[68:69] offset:288
	global_load_dwordx4 v[222:225], v185, s[60:61]
	global_load_dwordx4 v[226:229], v185, s[60:61] offset:64
	global_load_dwordx4 v[230:233], v185, s[60:61] offset:512
	global_load_dwordx4 v[234:237], v185, s[60:61] offset:576
	s_waitcnt vmcnt(12)
;     static __device__ __forceinline__ const void* rowptr(const void* b, size_t r, int ldc) { if constexpr (BASE_BF16) return (const bf16_t*)b + r * ldc; else return (const float*)b + r * ldc; }
;     static __device__ __forceinline__ void stq(bf16_t* p, f32x4 v) { u32x2 w; w.x = cvt_pk_bf16(v[0], v[1]); w.y = cvt_pk_bf16(v[2], v[3]); *(u32x2*)p = w; }
;     __device__ __forceinline__ void operator()(const f32x4 (&acc)[2][2][4][2], const Unit& u, int wr, int wc, int fr, int fq) const {
;     ...
;             for (int ai = 0; ai < 2; ++ai)
; #pragma unroll
;                 for (int m = 0; m < 4; ++m) { const int r = u.pm * BM + ai * HALF + wr * 64 + m * 16 + fr;
;                     const void* brow = (r < split_rows) ? rowptr(base_p, (size_t)r, ldc) : rowptr(base_s, (size_t)(r - split_rows), ldc);
;                     const float* grow = mod + (size_t)((r < split_rows) ? 0 : 1 + ((r - split_rows) >> 3)) * modld + goff;
;                     bf16_t* orow = out + (size_t)r * ldc;
; #pragma unroll
;                     for (int bj = 0; bj < 2; ++bj)
; #pragma unroll
;                         for (int n = 0; n < 2; ++n) { const int c = col0 + bj * HALF + n * 16;
;                             const f32x4 b = ldb(brow, c), g = *(const f32x4*)(grow + c);
;                             stq(orow + c, b + (g * gs) * acc[ai][bj][m][n]); }
;                     asm volatile("" ::: "memory"); }
	v_lshlrev_b32_e32 v142, 16, v190
	v_and_b32_e32 v143, 0xffff0000, v190
	v_lshlrev_b32_e32 v144, 16, v191
	v_and_b32_e32 v145, 0xffff0000, v191
	v_pk_fma_f32 v[142:143], v[198:199], v[62:63], v[142:143]
	v_pk_fma_f32 v[144:145], v[200:201], v[64:65], v[144:145]
	v_cvt_pk_bf16_f32 v188, v142, v143
	v_cvt_pk_bf16_f32 v189, v144, v145
	global_store_dwordx2 v138, v[188:189], s[68:69]
	v_lshlrev_b32_e32 v142, 16, v192
	v_and_b32_e32 v143, 0xffff0000, v192
	v_lshlrev_b32_e32 v144, 16, v193
	v_and_b32_e32 v145, 0xffff0000, v193
	v_pk_fma_f32 v[142:143], v[202:203], v[58:59], v[142:143]
	v_pk_fma_f32 v[144:145], v[204:205], v[60:61], v[144:145]
	v_cvt_pk_bf16_f32 v188, v142, v143
	v_cvt_pk_bf16_f32 v189, v144, v145
	global_store_dwordx2 v138, v[188:189], s[68:69] offset:32
	v_lshlrev_b32_e32 v142, 16, v194
	v_and_b32_e32 v143, 0xffff0000, v194
	v_lshlrev_b32_e32 v144, 16, v195
	v_and_b32_e32 v145, 0xffff0000, v195
	v_pk_fma_f32 v[142:143], v[206:207], v[54:55], v[142:143]
	v_pk_fma_f32 v[144:145], v[208:209], v[56:57], v[144:145]
	v_cvt_pk_bf16_f32 v188, v142, v143
	v_cvt_pk_bf16_f32 v189, v144, v145
	global_store_dwordx2 v138, v[188:189], s[68:69] offset:256
	v_lshlrev_b32_e32 v142, 16, v196
	v_and_b32_e32 v143, 0xffff0000, v196
	v_lshlrev_b32_e32 v144, 16, v197
	v_and_b32_e32 v145, 0xffff0000, v197
	v_pk_fma_f32 v[142:143], v[210:211], v[50:51], v[142:143]
	v_pk_fma_f32 v[144:145], v[212:213], v[52:53], v[144:145]
	v_cvt_pk_bf16_f32 v188, v142, v143
	v_cvt_pk_bf16_f32 v189, v144, v145
	global_store_dwordx2 v138, v[188:189], s[68:69] offset:288
	global_load_dwordx2 v[190:191], v140, s[68:69]
	global_load_dwordx2 v[192:193], v140, s[68:69] offset:32
	global_load_dwordx2 v[194:195], v140, s[68:69] offset:256
	global_load_dwordx2 v[196:197], v140, s[68:69] offset:288
	global_load_dwordx4 v[198:201], v186, s[60:61]
	global_load_dwordx4 v[202:205], v186, s[60:61] offset:64
	global_load_dwordx4 v[206:209], v186, s[60:61] offset:512
	global_load_dwordx4 v[210:213], v186, s[60:61] offset:576
	s_waitcnt vmcnt(12)
	v_lshlrev_b32_e32 v142, 16, v214
	v_and_b32_e32 v143, 0xffff0000, v214
	v_lshlrev_b32_e32 v144, 16, v215
	v_and_b32_e32 v145, 0xffff0000, v215
	v_pk_fma_f32 v[142:143], v[222:223], v[46:47], v[142:143]
	v_pk_fma_f32 v[144:145], v[224:225], v[48:49], v[144:145]
	v_cvt_pk_bf16_f32 v188, v142, v143
	v_cvt_pk_bf16_f32 v189, v144, v145
	global_store_dwordx2 v139, v[188:189], s[68:69]
	v_lshlrev_b32_e32 v142, 16, v216
	v_and_b32_e32 v143, 0xffff0000, v216
	v_lshlrev_b32_e32 v144, 16, v217
	v_and_b32_e32 v145, 0xffff0000, v217
	v_pk_fma_f32 v[142:143], v[226:227], v[42:43], v[142:143]
	v_pk_fma_f32 v[144:145], v[228:229], v[44:45], v[144:145]
	v_cvt_pk_bf16_f32 v188, v142, v143
	v_cvt_pk_bf16_f32 v189, v144, v145
	global_store_dwordx2 v139, v[188:189], s[68:69] offset:32
	v_lshlrev_b32_e32 v142, 16, v218
	v_and_b32_e32 v143, 0xffff0000, v218
	v_lshlrev_b32_e32 v144, 16, v219
	v_and_b32_e32 v145, 0xffff0000, v219
	v_pk_fma_f32 v[142:143], v[230:231], v[38:39], v[142:143]
	v_pk_fma_f32 v[144:145], v[232:233], v[40:41], v[144:145]
	v_cvt_pk_bf16_f32 v188, v142, v143
	v_cvt_pk_bf16_f32 v189, v144, v145
	global_store_dwordx2 v139, v[188:189], s[68:69] offset:256
	v_lshlrev_b32_e32 v142, 16, v220
	v_and_b32_e32 v143, 0xffff0000, v220
	v_lshlrev_b32_e32 v144, 16, v221
	v_and_b32_e32 v145, 0xffff0000, v221
	v_pk_fma_f32 v[142:143], v[234:235], v[34:35], v[142:143]
	v_pk_fma_f32 v[144:145], v[236:237], v[36:37], v[144:145]
	v_cvt_pk_bf16_f32 v188, v142, v143
	v_cvt_pk_bf16_f32 v189, v144, v145
	global_store_dwordx2 v139, v[188:189], s[68:69] offset:288
	global_load_dwordx2 v[214:215], v141, s[68:69]
	global_load_dwordx2 v[216:217], v141, s[68:69] offset:32
	global_load_dwordx2 v[218:219], v141, s[68:69] offset:256
	global_load_dwordx2 v[220:221], v141, s[68:69] offset:288
	global_load_dwordx4 v[222:225], v187, s[60:61]
	global_load_dwordx4 v[226:229], v187, s[60:61] offset:64
	global_load_dwordx4 v[230:233], v187, s[60:61] offset:512
	global_load_dwordx4 v[234:237], v187, s[60:61] offset:576
	s_waitcnt vmcnt(12)
;     static __device__ __forceinline__ const void* rowptr(const void* b, size_t r, int ldc) { if constexpr (BASE_BF16) return (const bf16_t*)b + r * ldc; else return (const float*)b + r * ldc; }
;     static __device__ __forceinline__ void stq(bf16_t* p, f32x4 v) { u32x2 w; w.x = cvt_pk_bf16(v[0], v[1]); w.y = cvt_pk_bf16(v[2], v[3]); *(u32x2*)p = w; }
;     __device__ __forceinline__ void operator()(const f32x4 (&acc)[2][2][4][2], const Unit& u, int wr, int wc, int fr, int fq) const {
;     ...
;             for (int ai = 0; ai < 2; ++ai)
; #pragma unroll
;                 for (int m = 0; m < 4; ++m) { const int r = u.pm * BM + ai * HALF + wr * 64 + m * 16 + fr;
;                     const void* brow = (r < split_rows) ? rowptr(base_p, (size_t)r, ldc) : rowptr(base_s, (size_t)(r - split_rows), ldc);
;                     const float* grow = mod + (size_t)((r < split_rows) ? 0 : 1 + ((r - split_rows) >> 3)) * modld + goff;
;                     bf16_t* orow = out + (size_t)r * ldc;
; #pragma unroll
;                     for (int bj = 0; bj < 2; ++bj)
; #pragma unroll
;                         for (int n = 0; n < 2; ++n) { const int c = col0 + bj * HALF + n * 16;
;                             const f32x4 b = ldb(brow, c), g = *(const f32x4*)(grow + c);
;                             stq(orow + c, b + (g * gs) * acc[ai][bj][m][n]); }
;                     asm volatile("" ::: "memory"); }
	v_lshlrev_b32_e32 v142, 16, v190
	v_and_b32_e32 v143, 0xffff0000, v190
	v_lshlrev_b32_e32 v144, 16, v191
	v_and_b32_e32 v145, 0xffff0000, v191
	v_pk_fma_f32 v[142:143], v[198:199], v[30:31], v[142:143]
	v_pk_fma_f32 v[144:145], v[200:201], v[32:33], v[144:145]
	v_cvt_pk_bf16_f32 v188, v142, v143
	v_cvt_pk_bf16_f32 v189, v144, v145
	global_store_dwordx2 v140, v[188:189], s[68:69]
	v_lshlrev_b32_e32 v142, 16, v192
	v_and_b32_e32 v143, 0xffff0000, v192
	v_lshlrev_b32_e32 v144, 16, v193
	v_and_b32_e32 v145, 0xffff0000, v193
	v_pk_fma_f32 v[142:143], v[202:203], v[26:27], v[142:143]
	v_pk_fma_f32 v[144:145], v[204:205], v[28:29], v[144:145]
	v_cvt_pk_bf16_f32 v188, v142, v143
	v_cvt_pk_bf16_f32 v189, v144, v145
	global_store_dwordx2 v140, v[188:189], s[68:69] offset:32
	v_lshlrev_b32_e32 v142, 16, v194
	v_and_b32_e32 v143, 0xffff0000, v194
	v_lshlrev_b32_e32 v144, 16, v195
	v_and_b32_e32 v145, 0xffff0000, v195
	v_pk_fma_f32 v[142:143], v[206:207], v[22:23], v[142:143]
	v_pk_fma_f32 v[144:145], v[208:209], v[24:25], v[144:145]
	v_cvt_pk_bf16_f32 v188, v142, v143
	v_cvt_pk_bf16_f32 v189, v144, v145
	global_store_dwordx2 v140, v[188:189], s[68:69] offset:256
	v_lshlrev_b32_e32 v142, 16, v196
	v_and_b32_e32 v143, 0xffff0000, v196
	v_lshlrev_b32_e32 v144, 16, v197
	v_and_b32_e32 v145, 0xffff0000, v197
	v_pk_fma_f32 v[142:143], v[210:211], v[18:19], v[142:143]
	v_pk_fma_f32 v[144:145], v[212:213], v[20:21], v[144:145]
	v_cvt_pk_bf16_f32 v188, v142, v143
	v_cvt_pk_bf16_f32 v189, v144, v145
	global_store_dwordx2 v140, v[188:189], s[68:69] offset:288
	s_waitcnt vmcnt(4)
	v_lshlrev_b32_e32 v142, 16, v214
	v_and_b32_e32 v143, 0xffff0000, v214
	v_lshlrev_b32_e32 v144, 16, v215
	v_and_b32_e32 v145, 0xffff0000, v215
	v_pk_fma_f32 v[142:143], v[222:223], v[14:15], v[142:143]
	v_pk_fma_f32 v[144:145], v[224:225], v[16:17], v[144:145]
	v_cvt_pk_bf16_f32 v188, v142, v143
	v_cvt_pk_bf16_f32 v189, v144, v145
	global_store_dwordx2 v141, v[188:189], s[68:69]
	v_lshlrev_b32_e32 v142, 16, v216
	v_and_b32_e32 v143, 0xffff0000, v216
	v_lshlrev_b32_e32 v144, 16, v217
	v_and_b32_e32 v145, 0xffff0000, v217
	v_pk_fma_f32 v[142:143], v[226:227], v[10:11], v[142:143]
	v_pk_fma_f32 v[144:145], v[228:229], v[12:13], v[144:145]
	v_cvt_pk_bf16_f32 v188, v142, v143
	v_cvt_pk_bf16_f32 v189, v144, v145
	global_store_dwordx2 v141, v[188:189], s[68:69] offset:32
	v_lshlrev_b32_e32 v142, 16, v218
	v_and_b32_e32 v143, 0xffff0000, v218
	v_lshlrev_b32_e32 v144, 16, v219
	v_and_b32_e32 v145, 0xffff0000, v219
	v_pk_fma_f32 v[142:143], v[230:231], v[6:7], v[142:143]
	v_pk_fma_f32 v[144:145], v[232:233], v[8:9], v[144:145]
	v_cvt_pk_bf16_f32 v188, v142, v143
	v_cvt_pk_bf16_f32 v189, v144, v145
	global_store_dwordx2 v141, v[188:189], s[68:69] offset:256
	v_lshlrev_b32_e32 v142, 16, v220
	v_and_b32_e32 v143, 0xffff0000, v220
	v_lshlrev_b32_e32 v144, 16, v221
	v_and_b32_e32 v145, 0xffff0000, v221
	v_pk_fma_f32 v[142:143], v[234:235], v[2:3], v[142:143]
	v_pk_fma_f32 v[144:145], v[236:237], v[4:5], v[144:145]
	v_cvt_pk_bf16_f32 v188, v142, v143
	v_cvt_pk_bf16_f32 v189, v144, v145
	global_store_dwordx2 v141, v[188:189], s[68:69] offset:288
	s_branch .LBB0_730
